# P1->P2 seam also uses the one-shot two-level barrier (own words); P2->P3 and P4->P5 keep the XCD-census barrier
# baseline (speedup 1.0000x reference)
; __device__ __forceinline__ unsigned xb_ld(unsigned* p)              { return __hip_atomic_load(p, __ATOMIC_RELAXED, __HIP_MEMORY_SCOPE_AGENT); }
; __device__ __forceinline__ unsigned xb_add(unsigned* p, unsigned v) { return __hip_atomic_fetch_add(p, v, __ATOMIC_RELAXED, __HIP_MEMORY_SCOPE_AGENT); }
; #define XB_SPIN(cond, bar) do { unsigned _sp = 0; while (cond) { __builtin_amdgcn_s_sleep(1); \
;     if ((++_sp & 255u) == 0u) { if (xb_ld(&(bar)[XB_TMO])) break; if (_sp > XB_SPIN_CAP) { atomicAdd(&(bar)[XB_TMO], 1u); break; } } } } while (0)
; __device__ __forceinline__ void xcd_barrier(const XcdBarrier& b) {
;     asm volatile("s_waitcnt vmcnt(0)" ::: "memory");
;     __syncthreads();
;     if (threadIdx.x == 0) {
;         unsigned* bar = b.bar;
;         __builtin_amdgcn_s_waitcnt(0);
;         unsigned nloc = b.st[0], nx = b.st[1];
;         if (nloc == 0u) { xcd_barrier_complete(bar, b.x, nloc, nx); b.st[0] = nloc; b.st[1] = nx; }
;         const unsigned old = xb_add(&bar[XB_XSUB(b.x)], 1u);
;         const unsigned gen = old / nloc;
;         if (old + 1u == (gen + 1u) * nloc) {
;             __builtin_amdgcn_fence(__ATOMIC_RELEASE, "agent");
;             asm volatile("s_waitcnt vmcnt(0)" ::: "memory");
;             const unsigned og = xb_add(&bar[XB_TOP], 1u);
;             const unsigned tg = og / nx;
;             if (og + 1u == (tg + 1u) * nx) xb_add(&bar[XB_TOPGEN], 1u);
;             else XB_SPIN(xb_ld(&bar[XB_TOPGEN]) == tg, bar);
;             __builtin_amdgcn_fence(__ATOMIC_ACQUIRE, "agent");
;             xb_add(&bar[XB_XGEN(b.x)], 1u);
;             asm volatile("s_waitcnt vmcnt(0)" ::: "memory");
;         } else {
;             XB_SPIN(xb_ld(&bar[XB_XGEN(b.x)]) == gen, bar);
;             __builtin_amdgcn_fence(__ATOMIC_ACQUIRE, "agent");
;             asm volatile("s_waitcnt vmcnt(0)" ::: "memory");
;         }
;     }
;     __syncthreads();
; }
.LBB0_162:
	s_cmp_gt_i32 s31, 2
	s_cselect_b64 s[4:5], -1, 0
	s_and_b64 s[6:7], s[62:63], s[4:5]
	s_andn2_b64 vcc, exec, s[6:7]
	s_cbranch_vccnz .LBB0_216
	s_waitcnt vmcnt(0)
	s_waitcnt vmcnt(0)
	s_barrier
	s_and_saveexec_b64 s[6:7], s[0:1]
	s_cbranch_execz .LBB0_215
	buffer_wbl2 sc1
	s_waitcnt vmcnt(0)
	s_add_u32 s8, s28, 0x84900
	s_addc_u32 s9, s29, 0
	s_and_b32 s10, s2, 7
	s_lshl_b32 s10, s10, 8
	s_add_u32 s10, s10, 0x85000
	s_add_u32 s10, s28, s10
	s_addc_u32 s11, s29, 0
	v_mov_b32_e32 v1, 0
	v_mov_b32_e32 v2, 1
	global_atomic_add v3, v1, v2, s[10:11] offset:32 sc0
	s_waitcnt vmcnt(0)
	v_readfirstlane_b32 s12, v3
	s_cmp_lg_u32 s12, 31
	s_cbranch_scc1 .Lgs1_member
	global_atomic_add v3, v1, v2, s[8:9] offset:32 sc0
	s_waitcnt vmcnt(0)
	v_readfirstlane_b32 s12, v3
	s_cmp_lg_u32 s12, 7
	s_cbranch_scc1 .Lgs1_leader_wait
	global_atomic_add v1, v2, s[8:9] offset:64
	s_branch .Lgs1_leader_go

; __device__ __forceinline__ unsigned xb_ld(unsigned* p)              { return __hip_atomic_load(p, __ATOMIC_RELAXED, __HIP_MEMORY_SCOPE_AGENT); }
; __device__ __forceinline__ void xcd_barrier_complete(unsigned* bar, unsigned x, unsigned& nloc, unsigned& nx) {
;     const unsigned G = gridDim.x * gridDim.y * gridDim.z;
;     unsigned sum, cnt, mine, sp = 0u;
;     for (;;) {
;         sum = 0u; cnt = 0u; mine = 0u;
; #pragma unroll
;         for (unsigned j = 0; j < 16; ++j) { const unsigned c = xb_ld(&bar[XB_XCNT(j)]); sum += c; cnt += (c > 0u) ? 1u : 0u; mine = (j == x) ? c : mine; }
;         if (sum == G) break;
;         __builtin_amdgcn_s_sleep(1);
;         if ((++sp & 255u) == 0u) { if (xb_ld(&bar[XB_TMO])) break; if (sp > XB_SPIN_CAP) { atomicAdd(&bar[XB_TMO], 1u); break; } }
;     }
;     nloc = mine > 0u ? mine : 1u; nx = cnt > 0u ? cnt : 1u;
; }
.Lgs1_top:
	s_sleep 1
	global_load_dword v3, v1, s[8:9] offset:64 sc1
	s_waitcnt vmcnt(0)
	v_readfirstlane_b32 s12, v3
	s_add_u32 s13, s13, 1
	s_cmp_lg_u32 s12, 0
	s_cbranch_scc1 .Lgs1_top_ok
	s_cmp_lt_u32 s13, 0x4000
	s_cbranch_scc1 .Lgs1_top

; __device__ __forceinline__ unsigned xb_ld(unsigned* p)              { return __hip_atomic_load(p, __ATOMIC_RELAXED, __HIP_MEMORY_SCOPE_AGENT); }
; __device__ __forceinline__ unsigned xb_add(unsigned* p, unsigned v) { return __hip_atomic_fetch_add(p, v, __ATOMIC_RELAXED, __HIP_MEMORY_SCOPE_AGENT); }
; #define XB_SPIN(cond, bar) do { unsigned _sp = 0; while (cond) { __builtin_amdgcn_s_sleep(1); \
;     if ((++_sp & 255u) == 0u) { if (xb_ld(&(bar)[XB_TMO])) break; if (_sp > XB_SPIN_CAP) { atomicAdd(&(bar)[XB_TMO], 1u); break; } } } } while (0)
; __device__ __forceinline__ void xcd_barrier_complete(unsigned* bar, unsigned x, unsigned& nloc, unsigned& nx) {
;     ...
;     nloc = mine > 0u ? mine : 1u; nx = cnt > 0u ? cnt : 1u;
; }
; __device__ __forceinline__ void xcd_barrier(const XcdBarrier& b) {
;     asm volatile("s_waitcnt vmcnt(0)" ::: "memory");
;     __syncthreads();
;     if (threadIdx.x == 0) {
;         unsigned* bar = b.bar;
;         __builtin_amdgcn_s_waitcnt(0);
;         unsigned nloc = b.st[0], nx = b.st[1];
;         if (nloc == 0u) { xcd_barrier_complete(bar, b.x, nloc, nx); b.st[0] = nloc; b.st[1] = nx; }
;         const unsigned old = xb_add(&bar[XB_XSUB(b.x)], 1u);
;         const unsigned gen = old / nloc;
;         if (old + 1u == (gen + 1u) * nloc) {
;             __builtin_amdgcn_fence(__ATOMIC_RELEASE, "agent");
;             asm volatile("s_waitcnt vmcnt(0)" ::: "memory");
;             const unsigned og = xb_add(&bar[XB_TOP], 1u);
;             const unsigned tg = og / nx;
;             if (og + 1u == (tg + 1u) * nx) xb_add(&bar[XB_TOPGEN], 1u);
;             else XB_SPIN(xb_ld(&bar[XB_TOPGEN]) == tg, bar);
;             __builtin_amdgcn_fence(__ATOMIC_ACQUIRE, "agent");
;             xb_add(&bar[XB_XGEN(b.x)], 1u);
;             asm volatile("s_waitcnt vmcnt(0)" ::: "memory");
;         } else {
;             XB_SPIN(xb_ld(&bar[XB_XGEN(b.x)]) == gen, bar);
;             __builtin_amdgcn_fence(__ATOMIC_ACQUIRE, "agent");
;             asm volatile("s_waitcnt vmcnt(0)" ::: "memory");
;         }
;     }
;     __syncthreads();
.Lgs1_grp_ok:
.Lgs1_done:
	s_waitcnt vmcnt(0)
	buffer_inv sc1
	s_waitcnt vmcnt(0)
